# grid barrier: non-leader workgroups poll the cross-XCD generation word directly (same expected generation) instead of the per-XCD relay word; each still does its own buffer_inv acquire
# speedup vs baseline: 1.0090x; 1.0047x over previous
; __device__ __forceinline__ unsigned xb_ld(unsigned* p)              { return __hip_atomic_load(p, __ATOMIC_RELAXED, __HIP_MEMORY_SCOPE_AGENT); }
; __device__ __forceinline__ unsigned xb_add(unsigned* p, unsigned v) { return __hip_atomic_fetch_add(p, v, __ATOMIC_RELAXED, __HIP_MEMORY_SCOPE_AGENT); }
; #define XB_SPIN(cond, bar) do { unsigned _sp = 0; while (cond) { __builtin_amdgcn_s_sleep(8); \
;     if ((++_sp & 255u) == 0u) { if (xb_ld(&(bar)[XB_TMO])) break; if (_sp > XB_SPIN_CAP) { atomicAdd(&(bar)[XB_TMO], 1u); break; } } } } while (0)
; __device__ __forceinline__ void xcd_barrier(const XcdBarrier& b) {
;     ...
;         const unsigned old = xb_add(&bar[XB_XSUB(b.x)], 1u);
;         const unsigned gen = old / nloc;
;         if (old + 1u == (gen + 1u) * nloc) {
;             __builtin_amdgcn_fence(__ATOMIC_RELEASE, "agent");
;             asm volatile("s_waitcnt vmcnt(0)" ::: "memory");
;             const unsigned og = xb_add(&bar[XB_TOP], 1u);
;             const unsigned tg = og / nx;
;             if (og + 1u == (tg + 1u) * nx) xb_add(&bar[XB_TOPGEN], 1u);
;             else XB_SPIN(xb_ld(&bar[XB_TOPGEN]) == tg, bar);
;             __builtin_amdgcn_fence(__ATOMIC_ACQUIRE, "agent");
;             xb_add(&bar[XB_XGEN(b.x)], 1u);
;             asm volatile("s_waitcnt vmcnt(0)" ::: "memory");
;         } else {
;             XB_SPIN(xb_ld(&bar[XB_XGEN(b.x)]) == gen, bar);
;             __builtin_amdgcn_fence(__ATOMIC_ACQUIRE, "agent");
;             asm volatile("s_waitcnt vmcnt(0)" ::: "memory");
.LBB0_344:
	s_or_b64 exec, exec, s[18:19]
	v_cvt_f32_u32_e32 v5, v3
	s_waitcnt vmcnt(0)
	v_readfirstlane_b32 s0, v4
	v_sub_u32_e32 v4, 0, v3
	v_rcp_iflag_f32_e32 v5, v5
	v_add_u32_e32 v6, s0, v0
	v_mul_f32_e32 v5, 0x4f7ffffe, v5
	v_cvt_u32_f32_e32 v5, v5
	v_mul_lo_u32 v0, v4, v5
	v_mul_hi_u32 v0, v5, v0
	v_add_u32_e32 v0, v5, v0
	v_mul_hi_u32 v0, v6, v0
	v_mul_lo_u32 v4, v0, v3
	v_sub_u32_e32 v4, v6, v4
	v_add_u32_e32 v5, 1, v0
	v_cmp_ge_u32_e32 vcc, v4, v3
	s_nop 1
	v_cndmask_b32_e32 v0, v0, v5, vcc
	v_sub_u32_e32 v5, v4, v3
	v_cndmask_b32_e32 v4, v4, v5, vcc
	v_add_u32_e32 v5, 1, v0
	v_cmp_ge_u32_e32 vcc, v4, v3
	v_add_u32_e32 v4, 1, v6
	s_nop 0
	v_cndmask_b32_e32 v0, v0, v5, vcc
	v_mul_lo_u32 v5, v3, v0
	v_add_u32_e32 v3, v5, v3
	v_cmp_ne_u32_e32 vcc, v4, v3
	s_and_saveexec_b64 s[0:1], vcc
	s_xor_b64 s[18:19], exec, s[0:1]
	s_cbranch_execz .LBB0_358
	v_readlane_b32 s0, v251, 58
	v_readlane_b32 s1, v251, 59
	s_waitcnt lgkmcnt(0)
	s_nop 3
	global_load_dword v2, v1, s[0:1] sc1
	s_waitcnt vmcnt(0)
	v_cmp_eq_u32_e32 vcc, v2, v0
	s_and_saveexec_b64 s[20:21], vcc
	s_cbranch_execz .LBB0_357
	s_mov_b32 s0, 1
	s_mov_b64 s[38:39], 0
	s_branch .LBB0_348

; __device__ __forceinline__ unsigned xb_ld(unsigned* p)              { return __hip_atomic_load(p, __ATOMIC_RELAXED, __HIP_MEMORY_SCOPE_AGENT); }
; __device__ __forceinline__ unsigned xb_add(unsigned* p, unsigned v) { return __hip_atomic_fetch_add(p, v, __ATOMIC_RELAXED, __HIP_MEMORY_SCOPE_AGENT); }
; #define XB_SPIN(cond, bar) do { unsigned _sp = 0; while (cond) { __builtin_amdgcn_s_sleep(8); \
;     if ((++_sp & 255u) == 0u) { if (xb_ld(&(bar)[XB_TMO])) break; if (_sp > XB_SPIN_CAP) { atomicAdd(&(bar)[XB_TMO], 1u); break; } } } } while (0)
; __device__ __forceinline__ void xcd_barrier(const XcdBarrier& b) {
;     ...
;         const unsigned old = xb_add(&bar[XB_XSUB(b.x)], 1u);
;         const unsigned gen = old / nloc;
;         if (old + 1u == (gen + 1u) * nloc) {
;             __builtin_amdgcn_fence(__ATOMIC_RELEASE, "agent");
;             asm volatile("s_waitcnt vmcnt(0)" ::: "memory");
;             const unsigned og = xb_add(&bar[XB_TOP], 1u);
;             const unsigned tg = og / nx;
;             if (og + 1u == (tg + 1u) * nx) xb_add(&bar[XB_TOPGEN], 1u);
;             else XB_SPIN(xb_ld(&bar[XB_TOPGEN]) == tg, bar);
;             __builtin_amdgcn_fence(__ATOMIC_ACQUIRE, "agent");
;             xb_add(&bar[XB_XGEN(b.x)], 1u);
;             asm volatile("s_waitcnt vmcnt(0)" ::: "memory");
;         } else {
;             XB_SPIN(xb_ld(&bar[XB_XGEN(b.x)]) == gen, bar);
;             __builtin_amdgcn_fence(__ATOMIC_ACQUIRE, "agent");
;             asm volatile("s_waitcnt vmcnt(0)" ::: "memory");
.LBB0_438:
	s_or_b64 exec, exec, s[12:13]
	v_cvt_f32_u32_e32 v5, v3
	s_waitcnt vmcnt(0)
	v_readfirstlane_b32 s0, v4
	v_sub_u32_e32 v4, 0, v3
	v_rcp_iflag_f32_e32 v5, v5
	v_add_u32_e32 v6, s0, v0
	v_mul_f32_e32 v5, 0x4f7ffffe, v5
	v_cvt_u32_f32_e32 v5, v5
	v_mul_lo_u32 v0, v4, v5
	v_mul_hi_u32 v0, v5, v0
	v_add_u32_e32 v0, v5, v0
	v_mul_hi_u32 v0, v6, v0
	v_mul_lo_u32 v4, v0, v3
	v_sub_u32_e32 v4, v6, v4
	v_add_u32_e32 v5, 1, v0
	v_cmp_ge_u32_e32 vcc, v4, v3
	s_nop 1
	v_cndmask_b32_e32 v0, v0, v5, vcc
	v_sub_u32_e32 v5, v4, v3
	v_cndmask_b32_e32 v4, v4, v5, vcc
	v_add_u32_e32 v5, 1, v0
	v_cmp_ge_u32_e32 vcc, v4, v3
	v_add_u32_e32 v4, 1, v6
	s_nop 0
	v_cndmask_b32_e32 v0, v0, v5, vcc
	v_mul_lo_u32 v5, v3, v0
	v_add_u32_e32 v3, v5, v3
	v_cmp_ne_u32_e32 vcc, v4, v3
	s_and_saveexec_b64 s[0:1], vcc
	s_xor_b64 s[12:13], exec, s[0:1]
	s_cbranch_execz .LBB0_452
	v_readlane_b32 s0, v251, 58
	v_readlane_b32 s1, v251, 59
	s_waitcnt lgkmcnt(0)
	s_nop 3
	global_load_dword v2, v1, s[0:1] sc1
	s_waitcnt vmcnt(0)
	v_cmp_eq_u32_e32 vcc, v2, v0
	s_and_saveexec_b64 s[14:15], vcc
	s_cbranch_execz .LBB0_451
	s_mov_b32 s0, 1
	s_mov_b64 s[18:19], 0
	s_branch .LBB0_442

; __device__ __forceinline__ unsigned xb_ld(unsigned* p)              { return __hip_atomic_load(p, __ATOMIC_RELAXED, __HIP_MEMORY_SCOPE_AGENT); }
; __device__ __forceinline__ unsigned xb_add(unsigned* p, unsigned v) { return __hip_atomic_fetch_add(p, v, __ATOMIC_RELAXED, __HIP_MEMORY_SCOPE_AGENT); }
; #define XB_SPIN(cond, bar) do { unsigned _sp = 0; while (cond) { __builtin_amdgcn_s_sleep(8); \
;     if ((++_sp & 255u) == 0u) { if (xb_ld(&(bar)[XB_TMO])) break; if (_sp > XB_SPIN_CAP) { atomicAdd(&(bar)[XB_TMO], 1u); break; } } } } while (0)
; __device__ __forceinline__ void xcd_barrier(const XcdBarrier& b) {
;     ...
;         const unsigned old = xb_add(&bar[XB_XSUB(b.x)], 1u);
;         const unsigned gen = old / nloc;
;         if (old + 1u == (gen + 1u) * nloc) {
;             __builtin_amdgcn_fence(__ATOMIC_RELEASE, "agent");
;             asm volatile("s_waitcnt vmcnt(0)" ::: "memory");
;             const unsigned og = xb_add(&bar[XB_TOP], 1u);
;             const unsigned tg = og / nx;
;             if (og + 1u == (tg + 1u) * nx) xb_add(&bar[XB_TOPGEN], 1u);
;             else XB_SPIN(xb_ld(&bar[XB_TOPGEN]) == tg, bar);
;             __builtin_amdgcn_fence(__ATOMIC_ACQUIRE, "agent");
;             xb_add(&bar[XB_XGEN(b.x)], 1u);
;             asm volatile("s_waitcnt vmcnt(0)" ::: "memory");
;         } else {
;             XB_SPIN(xb_ld(&bar[XB_XGEN(b.x)]) == gen, bar);
;             __builtin_amdgcn_fence(__ATOMIC_ACQUIRE, "agent");
;             asm volatile("s_waitcnt vmcnt(0)" ::: "memory");
.LBB0_1404:
	s_or_b64 exec, exec, s[12:13]
	v_cvt_f32_u32_e32 v5, v3
	s_waitcnt vmcnt(0)
	v_readfirstlane_b32 s0, v4
	v_sub_u32_e32 v4, 0, v3
	v_rcp_iflag_f32_e32 v5, v5
	v_add_u32_e32 v6, s0, v0
	v_mul_f32_e32 v5, 0x4f7ffffe, v5
	v_cvt_u32_f32_e32 v5, v5
	v_mul_lo_u32 v0, v4, v5
	v_mul_hi_u32 v0, v5, v0
	v_add_u32_e32 v0, v5, v0
	v_mul_hi_u32 v0, v6, v0
	v_mul_lo_u32 v4, v0, v3
	v_sub_u32_e32 v4, v6, v4
	v_add_u32_e32 v5, 1, v0
	v_cmp_ge_u32_e32 vcc, v4, v3
	s_nop 1
	v_cndmask_b32_e32 v0, v0, v5, vcc
	v_sub_u32_e32 v5, v4, v3
	v_cndmask_b32_e32 v4, v4, v5, vcc
	v_add_u32_e32 v5, 1, v0
	v_cmp_ge_u32_e32 vcc, v4, v3
	v_add_u32_e32 v4, 1, v6
	s_nop 0
	v_cndmask_b32_e32 v0, v0, v5, vcc
	v_mul_lo_u32 v5, v3, v0
	v_add_u32_e32 v3, v5, v3
	v_cmp_ne_u32_e32 vcc, v4, v3
	s_and_saveexec_b64 s[0:1], vcc
	s_xor_b64 s[12:13], exec, s[0:1]
	s_cbranch_execz .LBB0_1418
	v_readlane_b32 s0, v251, 58
	v_readlane_b32 s1, v251, 59
	s_waitcnt lgkmcnt(0)
	s_nop 3
	global_load_dword v2, v1, s[0:1] sc1
	s_waitcnt vmcnt(0)
	v_cmp_eq_u32_e32 vcc, v2, v0
	s_and_saveexec_b64 s[14:15], vcc
	s_cbranch_execz .LBB0_1417
	s_mov_b32 s30, s42
	s_mov_b32 s0, 1
	s_mov_b64 s[18:19], 0
	s_branch .LBB0_1408
